# GEMM K-loops: loader segment runs at priority 1, MFMA block at priority 0 (inverted flips)
# baseline (speedup 1.0000x reference)
.LBB0_290:
	s_add_i32 s29, s30, 2
	s_add_u32 s31, s56, 0x80
	s_addc_u32 s35, s57, 0
	s_add_i32 s72, 0, 0x10000
	s_cmp_eq_u32 s67, s30
	s_cselect_b32 s55, s1, s35
	s_cselect_b32 s54, s0, s31
	v_add_u32_e32 v144, s72, v147
	s_cselect_b32 s31, s53, s19
	s_cselect_b32 s30, s52, s18
	s_add_i32 s35, 0, 0x14000
	ds_read_b128 v[140:143], v144
	ds_read_b128 v[176:179], v144 offset:1024
	ds_read_b128 v[180:183], v144 offset:2048
	ds_read_b128 v[184:187], v144 offset:3072
	v_add_u32_e32 v144, s35, v147
	ds_read_b128 v[188:191], v144
	ds_read_b128 v[192:195], v144 offset:1024
	ds_read_b128 v[196:199], v144 offset:2048
	ds_read_b128 v[200:203], v144 offset:3072
	v_lshl_add_u64 v[144:145], s[56:57], 0, v[136:137]
	s_add_i32 m0, s58, 0xc000
	ds_read_b128 v[204:207], v169
	ds_read_b128 v[208:211], v169 offset:1024
	ds_read_b128 v[212:215], v169 offset:2048
	ds_read_b128 v[216:219], v169 offset:3072
	ds_read_b128 v[220:223], v169 offset:4096
	ds_read_b128 v[224:227], v169 offset:5120
	ds_read_b128 v[228:231], v169 offset:6144
	ds_read_b128 v[232:235], v169 offset:7168
	global_load_lds_dwordx4 v[144:145], off
	v_lshl_add_u64 v[144:145], s[56:57], 0, v[138:139]
	s_add_i32 m0, s58, 0xe000
	s_nop 0
	global_load_lds_dwordx4 v[144:145], off
	s_waitcnt vmcnt(8)
	s_waitcnt lgkmcnt(0)
	s_barrier
	s_setprio 0
	s_waitcnt lgkmcnt(0)
	v_mfma_f32_16x16x32_bf16 v[126:129], v[140:143], v[204:207], v[126:129]
	v_mfma_f32_16x16x32_bf16 v[114:117], v[180:183], v[204:207], v[114:117]
	v_mfma_f32_16x16x32_bf16 v[106:109], v[140:143], v[212:215], v[106:109]
	v_mfma_f32_16x16x32_bf16 v[98:101], v[180:183], v[212:215], v[98:101]
	v_mfma_f32_16x16x32_bf16 v[90:93], v[140:143], v[220:223], v[90:93]
	v_mfma_f32_16x16x32_bf16 v[82:85], v[180:183], v[220:223], v[82:85]
	v_mfma_f32_16x16x32_bf16 v[74:77], v[140:143], v[228:231], v[74:77]
	v_mfma_f32_16x16x32_bf16 v[54:57], v[180:183], v[228:231], v[54:57]
	v_mfma_f32_16x16x32_bf16 v[126:129], v[176:179], v[208:211], v[126:129]
	v_mfma_f32_16x16x32_bf16 v[114:117], v[184:187], v[208:211], v[114:117]
	v_mfma_f32_16x16x32_bf16 v[106:109], v[176:179], v[216:219], v[106:109]
	v_mfma_f32_16x16x32_bf16 v[98:101], v[184:187], v[216:219], v[98:101]
	v_mfma_f32_16x16x32_bf16 v[90:93], v[176:179], v[224:227], v[90:93]
	v_mfma_f32_16x16x32_bf16 v[82:85], v[184:187], v[224:227], v[82:85]
	v_mfma_f32_16x16x32_bf16 v[74:77], v[176:179], v[232:235], v[74:77]
	v_mfma_f32_16x16x32_bf16 v[54:57], v[184:187], v[232:235], v[54:57]
	v_mfma_f32_16x16x32_bf16 v[118:121], v[188:191], v[204:207], v[118:121]
	v_mfma_f32_16x16x32_bf16 v[122:125], v[196:199], v[204:207], v[122:125]
	v_mfma_f32_16x16x32_bf16 v[102:105], v[188:191], v[212:215], v[102:105]
	v_mfma_f32_16x16x32_bf16 v[110:113], v[196:199], v[212:215], v[110:113]
	v_mfma_f32_16x16x32_bf16 v[86:89], v[188:191], v[220:223], v[86:89]
	v_mfma_f32_16x16x32_bf16 v[94:97], v[196:199], v[220:223], v[94:97]
	v_mfma_f32_16x16x32_bf16 v[70:73], v[188:191], v[228:231], v[70:73]
	v_mfma_f32_16x16x32_bf16 v[78:81], v[196:199], v[228:231], v[78:81]
	v_mfma_f32_16x16x32_bf16 v[118:121], v[192:195], v[208:211], v[118:121]
	v_mfma_f32_16x16x32_bf16 v[122:125], v[200:203], v[208:211], v[122:125]
	v_mfma_f32_16x16x32_bf16 v[102:105], v[192:195], v[216:219], v[102:105]
	v_mfma_f32_16x16x32_bf16 v[110:113], v[200:203], v[216:219], v[110:113]
	v_mfma_f32_16x16x32_bf16 v[86:89], v[192:195], v[224:227], v[86:89]
	v_mfma_f32_16x16x32_bf16 v[94:97], v[200:203], v[224:227], v[94:97]
	v_mfma_f32_16x16x32_bf16 v[70:73], v[192:195], v[232:235], v[70:73]
	v_mfma_f32_16x16x32_bf16 v[78:81], v[200:203], v[232:235], v[78:81]
	s_setprio 1
	s_barrier
	s_add_i32 s72, s72, s23
	v_lshl_add_u64 v[144:145], s[30:31], 0, v[0:1]
	s_mov_b32 m0, s72
	ds_read_b128 v[204:207], v169 offset:16384
	ds_read_b128 v[208:211], v169 offset:17408
	ds_read_b128 v[212:215], v169 offset:18432
	ds_read_b128 v[216:219], v169 offset:19456
	ds_read_b128 v[220:223], v169 offset:20480
	ds_read_b128 v[224:227], v169 offset:21504
	ds_read_b128 v[228:231], v169 offset:22528
	ds_read_b128 v[232:235], v169 offset:23552
	global_load_lds_dwordx4 v[144:145], off
	s_add_i32 m0, s72, 0x2000
	v_lshl_add_u64 v[236:237], s[30:31], 0, v[134:135]
	s_add_u32 s30, s30, s80
	s_addc_u32 s31, s31, 0
	s_add_i32 s35, s35, s23
	global_load_lds_dwordx4 v[236:237], off
	v_lshl_add_u64 v[238:239], s[30:31], 0, v[0:1]
	s_mov_b32 m0, s35
	v_lshl_add_u64 v[240:241], s[30:31], 0, v[134:135]
	global_load_lds_dwordx4 v[238:239], off
	s_add_i32 m0, s35, 0x2000
	v_lshl_add_u64 v[242:243], s[54:55], 0, v[130:131]
	global_load_lds_dwordx4 v[240:241], off
	s_mov_b32 m0, s58
	v_lshl_add_u64 v[244:245], s[54:55], 0, v[132:133]
	global_load_lds_dwordx4 v[242:243], off
	s_mov_b32 m0, s59
	s_nop 0
	global_load_lds_dwordx4 v[244:245], off
	s_waitcnt vmcnt(8)
	s_waitcnt lgkmcnt(0)
	s_barrier
	s_setprio 0
	s_waitcnt lgkmcnt(0)
	v_mfma_f32_16x16x32_bf16 v[58:61], v[140:143], v[204:207], v[58:61]
	v_mfma_f32_16x16x32_bf16 v[62:65], v[180:183], v[204:207], v[62:65]
	v_mfma_f32_16x16x32_bf16 v[38:41], v[140:143], v[212:215], v[38:41]
	v_mfma_f32_16x16x32_bf16 v[42:45], v[180:183], v[212:215], v[42:45]
	v_mfma_f32_16x16x32_bf16 v[18:21], v[140:143], v[220:223], v[18:21]
	v_mfma_f32_16x16x32_bf16 v[26:29], v[180:183], v[220:223], v[26:29]
	v_mfma_f32_16x16x32_bf16 v[2:5], v[140:143], v[228:231], v[2:5]
	v_mfma_f32_16x16x32_bf16 v[6:9], v[180:183], v[228:231], v[6:9]
	v_mfma_f32_16x16x32_bf16 v[58:61], v[176:179], v[208:211], v[58:61]
	v_mfma_f32_16x16x32_bf16 v[62:65], v[184:187], v[208:211], v[62:65]
	v_mfma_f32_16x16x32_bf16 v[38:41], v[176:179], v[216:219], v[38:41]
	v_mfma_f32_16x16x32_bf16 v[42:45], v[184:187], v[216:219], v[42:45]
	v_mfma_f32_16x16x32_bf16 v[18:21], v[176:179], v[224:227], v[18:21]
	v_mfma_f32_16x16x32_bf16 v[26:29], v[184:187], v[224:227], v[26:29]
	v_mfma_f32_16x16x32_bf16 v[2:5], v[176:179], v[232:235], v[2:5]
	v_mfma_f32_16x16x32_bf16 v[6:9], v[184:187], v[232:235], v[6:9]
	v_mfma_f32_16x16x32_bf16 v[50:53], v[188:191], v[204:207], v[50:53]
	v_mfma_f32_16x16x32_bf16 v[66:69], v[196:199], v[204:207], v[66:69]
	v_mfma_f32_16x16x32_bf16 v[34:37], v[188:191], v[212:215], v[34:37]
	v_mfma_f32_16x16x32_bf16 v[46:49], v[196:199], v[212:215], v[46:49]
	v_mfma_f32_16x16x32_bf16 v[14:17], v[188:191], v[220:223], v[14:17]
	v_mfma_f32_16x16x32_bf16 v[30:33], v[196:199], v[220:223], v[30:33]
	v_mfma_f32_16x16x32_bf16 v[10:13], v[188:191], v[228:231], v[10:13]
	v_mfma_f32_16x16x32_bf16 v[22:25], v[196:199], v[228:231], v[22:25]
	v_mfma_f32_16x16x32_bf16 v[50:53], v[192:195], v[208:211], v[50:53]
	v_mfma_f32_16x16x32_bf16 v[66:69], v[200:203], v[208:211], v[66:69]
	v_mfma_f32_16x16x32_bf16 v[34:37], v[192:195], v[216:219], v[34:37]
	v_mfma_f32_16x16x32_bf16 v[46:49], v[200:203], v[216:219], v[46:49]
	v_mfma_f32_16x16x32_bf16 v[14:17], v[192:195], v[224:227], v[14:17]
	v_mfma_f32_16x16x32_bf16 v[30:33], v[200:203], v[224:227], v[30:33]
	v_mfma_f32_16x16x32_bf16 v[10:13], v[192:195], v[232:235], v[10:13]
	v_mfma_f32_16x16x32_bf16 v[22:25], v[200:203], v[232:235], v[22:25]
	s_setprio 1
	s_barrier
	s_add_i32 s35, 0, 0x18000
	s_add_i32 s72, 0, 0x1c000
	v_add_u32_e32 v184, s35, v147
	v_add_u32_e32 v200, s72, v147
	ds_read_b128 v[140:143], v184
	ds_read_b128 v[176:179], v184 offset:1024
	ds_read_b128 v[180:183], v184 offset:2048
	ds_read_b128 v[184:187], v184 offset:3072
	ds_read_b128 v[188:191], v200
	ds_read_b128 v[192:195], v200 offset:1024
	ds_read_b128 v[196:199], v200 offset:2048
	ds_read_b128 v[200:203], v200 offset:3072
	s_add_u32 s30, s54, s80
	s_addc_u32 s31, s55, 0
	s_mov_b32 m0, s60
	v_lshl_add_u64 v[246:247], s[30:31], 0, v[130:131]
	ds_read_b128 v[204:207], v169 offset:32768
	ds_read_b128 v[208:211], v169 offset:33792
	ds_read_b128 v[212:215], v169 offset:34816
	ds_read_b128 v[216:219], v169 offset:35840
	ds_read_b128 v[220:223], v169 offset:36864
	ds_read_b128 v[224:227], v169 offset:37888
	ds_read_b128 v[228:231], v169 offset:38912
	ds_read_b128 v[232:235], v169 offset:39936
	global_load_lds_dwordx4 v[246:247], off
	v_lshl_add_u64 v[246:247], s[30:31], 0, v[132:133]
	s_mov_b32 m0, s61
	s_nop 0
	global_load_lds_dwordx4 v[246:247], off
	s_waitcnt vmcnt(8)
	s_waitcnt lgkmcnt(0)
	s_barrier
	s_setprio 0
	s_waitcnt lgkmcnt(0)
	v_mfma_f32_16x16x32_bf16 v[126:129], v[140:143], v[204:207], v[126:129]
	v_mfma_f32_16x16x32_bf16 v[114:117], v[180:183], v[204:207], v[114:117]
	v_mfma_f32_16x16x32_bf16 v[106:109], v[140:143], v[212:215], v[106:109]
	v_mfma_f32_16x16x32_bf16 v[98:101], v[180:183], v[212:215], v[98:101]
	v_mfma_f32_16x16x32_bf16 v[90:93], v[140:143], v[220:223], v[90:93]
	v_mfma_f32_16x16x32_bf16 v[82:85], v[180:183], v[220:223], v[82:85]
	v_mfma_f32_16x16x32_bf16 v[74:77], v[140:143], v[228:231], v[74:77]
	v_mfma_f32_16x16x32_bf16 v[54:57], v[180:183], v[228:231], v[54:57]
	v_mfma_f32_16x16x32_bf16 v[126:129], v[176:179], v[208:211], v[126:129]
	v_mfma_f32_16x16x32_bf16 v[114:117], v[184:187], v[208:211], v[114:117]
	v_mfma_f32_16x16x32_bf16 v[106:109], v[176:179], v[216:219], v[106:109]
	v_mfma_f32_16x16x32_bf16 v[98:101], v[184:187], v[216:219], v[98:101]
	v_mfma_f32_16x16x32_bf16 v[90:93], v[176:179], v[224:227], v[90:93]
	v_mfma_f32_16x16x32_bf16 v[82:85], v[184:187], v[224:227], v[82:85]
	v_mfma_f32_16x16x32_bf16 v[74:77], v[176:179], v[232:235], v[74:77]
	v_mfma_f32_16x16x32_bf16 v[54:57], v[184:187], v[232:235], v[54:57]
	v_mfma_f32_16x16x32_bf16 v[118:121], v[188:191], v[204:207], v[118:121]
	v_mfma_f32_16x16x32_bf16 v[122:125], v[196:199], v[204:207], v[122:125]
	v_mfma_f32_16x16x32_bf16 v[102:105], v[188:191], v[212:215], v[102:105]
	v_mfma_f32_16x16x32_bf16 v[110:113], v[196:199], v[212:215], v[110:113]
	v_mfma_f32_16x16x32_bf16 v[86:89], v[188:191], v[220:223], v[86:89]
	v_mfma_f32_16x16x32_bf16 v[94:97], v[196:199], v[220:223], v[94:97]
	v_mfma_f32_16x16x32_bf16 v[70:73], v[188:191], v[228:231], v[70:73]
	v_mfma_f32_16x16x32_bf16 v[78:81], v[196:199], v[228:231], v[78:81]
	v_mfma_f32_16x16x32_bf16 v[118:121], v[192:195], v[208:211], v[118:121]
	v_mfma_f32_16x16x32_bf16 v[122:125], v[200:203], v[208:211], v[122:125]
	v_mfma_f32_16x16x32_bf16 v[102:105], v[192:195], v[216:219], v[102:105]
	v_mfma_f32_16x16x32_bf16 v[110:113], v[200:203], v[216:219], v[110:113]
	v_mfma_f32_16x16x32_bf16 v[86:89], v[192:195], v[224:227], v[86:89]
	v_mfma_f32_16x16x32_bf16 v[94:97], v[200:203], v[224:227], v[94:97]
	v_mfma_f32_16x16x32_bf16 v[70:73], v[192:195], v[232:235], v[70:73]
	v_mfma_f32_16x16x32_bf16 v[78:81], v[200:203], v[232:235], v[78:81]
	s_setprio 1
	s_barrier
	s_add_i32 s30, s35, s23
	v_lshl_add_u64 v[144:145], v[144:145], 0, s[94:95]
	s_mov_b32 m0, s30
	ds_read_b128 v[204:207], v169 offset:49152
	ds_read_b128 v[208:211], v169 offset:50176
	ds_read_b128 v[212:215], v169 offset:51200
	ds_read_b128 v[216:219], v169 offset:52224
	ds_read_b128 v[220:223], v169 offset:53248
	ds_read_b128 v[224:227], v169 offset:54272
	ds_read_b128 v[228:231], v169 offset:55296
	ds_read_b128 v[232:235], v169 offset:56320
	global_load_lds_dwordx4 v[144:145], off
	v_lshl_add_u64 v[144:145], v[236:237], 0, s[94:95]
	s_add_i32 m0, s30, 0x2000
	s_add_i32 s30, s72, s23
	global_load_lds_dwordx4 v[144:145], off
	v_lshl_add_u64 v[144:145], v[238:239], 0, s[94:95]
	s_mov_b32 m0, s30
	s_nop 0
	global_load_lds_dwordx4 v[144:145], off
	v_lshl_add_u64 v[144:145], v[240:241], 0, s[94:95]
	s_add_i32 m0, s30, 0x2000
	s_nop 0
	global_load_lds_dwordx4 v[144:145], off
	v_lshl_add_u64 v[144:145], v[242:243], 0, s[94:95]
	s_mov_b32 m0, s64
	s_nop 0
	global_load_lds_dwordx4 v[144:145], off
	v_lshl_add_u64 v[144:145], v[244:245], 0, s[94:95]
	s_mov_b32 m0, s65
	s_nop 0
	global_load_lds_dwordx4 v[144:145], off
	s_waitcnt vmcnt(8)
	s_waitcnt lgkmcnt(0)
	s_barrier
	s_setprio 0
	s_waitcnt lgkmcnt(0)
	v_mfma_f32_16x16x32_bf16 v[58:61], v[140:143], v[204:207], v[58:61]
	v_mfma_f32_16x16x32_bf16 v[62:65], v[180:183], v[204:207], v[62:65]
	v_mfma_f32_16x16x32_bf16 v[38:41], v[140:143], v[212:215], v[38:41]
	v_mfma_f32_16x16x32_bf16 v[42:45], v[180:183], v[212:215], v[42:45]
	v_mfma_f32_16x16x32_bf16 v[18:21], v[140:143], v[220:223], v[18:21]
	v_mfma_f32_16x16x32_bf16 v[26:29], v[180:183], v[220:223], v[26:29]
	v_mfma_f32_16x16x32_bf16 v[2:5], v[140:143], v[228:231], v[2:5]
	v_mfma_f32_16x16x32_bf16 v[6:9], v[180:183], v[228:231], v[6:9]
	v_mfma_f32_16x16x32_bf16 v[58:61], v[176:179], v[208:211], v[58:61]
	v_mfma_f32_16x16x32_bf16 v[62:65], v[184:187], v[208:211], v[62:65]
	v_mfma_f32_16x16x32_bf16 v[38:41], v[176:179], v[216:219], v[38:41]
	v_mfma_f32_16x16x32_bf16 v[42:45], v[184:187], v[216:219], v[42:45]
	v_mfma_f32_16x16x32_bf16 v[18:21], v[176:179], v[224:227], v[18:21]
	v_mfma_f32_16x16x32_bf16 v[26:29], v[184:187], v[224:227], v[26:29]
	v_mfma_f32_16x16x32_bf16 v[2:5], v[176:179], v[232:235], v[2:5]
	v_mfma_f32_16x16x32_bf16 v[6:9], v[184:187], v[232:235], v[6:9]
	v_mfma_f32_16x16x32_bf16 v[50:53], v[188:191], v[204:207], v[50:53]
	v_mfma_f32_16x16x32_bf16 v[66:69], v[196:199], v[204:207], v[66:69]
	v_mfma_f32_16x16x32_bf16 v[34:37], v[188:191], v[212:215], v[34:37]
	v_mfma_f32_16x16x32_bf16 v[46:49], v[196:199], v[212:215], v[46:49]
	v_mfma_f32_16x16x32_bf16 v[14:17], v[188:191], v[220:223], v[14:17]
	v_mfma_f32_16x16x32_bf16 v[30:33], v[196:199], v[220:223], v[30:33]
	v_mfma_f32_16x16x32_bf16 v[10:13], v[188:191], v[228:231], v[10:13]
	v_mfma_f32_16x16x32_bf16 v[22:25], v[196:199], v[228:231], v[22:25]
	v_mfma_f32_16x16x32_bf16 v[50:53], v[192:195], v[208:211], v[50:53]
	v_mfma_f32_16x16x32_bf16 v[66:69], v[200:203], v[208:211], v[66:69]
	v_mfma_f32_16x16x32_bf16 v[34:37], v[192:195], v[216:219], v[34:37]
	v_mfma_f32_16x16x32_bf16 v[46:49], v[200:203], v[216:219], v[46:49]
	v_mfma_f32_16x16x32_bf16 v[14:17], v[192:195], v[224:227], v[14:17]
	v_mfma_f32_16x16x32_bf16 v[30:33], v[200:203], v[224:227], v[30:33]
	v_mfma_f32_16x16x32_bf16 v[10:13], v[192:195], v[232:235], v[10:13]
	v_mfma_f32_16x16x32_bf16 v[22:25], v[200:203], v[232:235], v[22:25]
	s_setprio 1
	s_barrier
	s_add_u32 s56, s56, 0x100
	s_addc_u32 s57, s57, 0
	s_add_u32 s18, s18, 0x100
	s_addc_u32 s19, s19, 0
	s_cmp_ge_u32 s29, s66
	s_mov_b32 s30, s29
	s_cbranch_scc0 .LBB0_290
	s_and_b64 vcc, exec, s[20:21]
	s_cbranch_vccz .LBB0_293
	s_barrier

.LBB0_334:
	s_add_i32 s66, s20, 2
	s_add_u32 s67, s16, 0x80
	s_addc_u32 s21, s17, 0
	s_add_i32 s72, 0, 0x10000
	s_cmp_eq_u32 s58, s20
	s_cselect_b32 s21, s1, s21
	s_cselect_b32 s20, s0, s67
	v_add_u32_e32 v140, s72, v143
	s_cselect_b32 s71, s15, s65
	s_cselect_b32 s70, s14, s64
	s_add_i32 s67, 0, 0x14000
	ds_read_b128 v[160:163], v140
	ds_read_b128 v[164:167], v140 offset:1024
	ds_read_b128 v[168:171], v140 offset:2048
	ds_read_b128 v[172:175], v140 offset:3072
	v_add_u32_e32 v140, s67, v143
	ds_read_b128 v[176:179], v140
	ds_read_b128 v[180:183], v140 offset:1024
	ds_read_b128 v[184:187], v140 offset:2048
	ds_read_b128 v[188:191], v140 offset:3072
	v_lshl_add_u64 v[140:141], s[16:17], 0, v[136:137]
	s_add_i32 m0, s19, 0xc000
	ds_read_b128 v[192:195], v146
	ds_read_b128 v[196:199], v146 offset:1024
	ds_read_b128 v[200:203], v146 offset:2048
	ds_read_b128 v[204:207], v146 offset:3072
	ds_read_b128 v[208:211], v146 offset:4096
	ds_read_b128 v[212:215], v146 offset:5120
	ds_read_b128 v[216:219], v146 offset:6144
	ds_read_b128 v[220:223], v146 offset:7168
	global_load_lds_dwordx4 v[140:141], off
	v_lshl_add_u64 v[140:141], s[16:17], 0, v[138:139]
	s_add_i32 m0, s19, 0xe000
	s_nop 0
	global_load_lds_dwordx4 v[140:141], off
	s_waitcnt vmcnt(8)
	s_waitcnt lgkmcnt(0)
	s_barrier
	s_setprio 0
	s_waitcnt lgkmcnt(0)
	v_mfma_f32_16x16x32_bf16 v[126:129], v[160:163], v[192:195], v[126:129]
	v_mfma_f32_16x16x32_bf16 v[122:125], v[168:171], v[192:195], v[122:125]
	v_mfma_f32_16x16x32_bf16 v[110:113], v[160:163], v[200:203], v[110:113]
	v_mfma_f32_16x16x32_bf16 v[106:109], v[168:171], v[200:203], v[106:109]
	v_mfma_f32_16x16x32_bf16 v[94:97], v[160:163], v[208:211], v[94:97]
	v_mfma_f32_16x16x32_bf16 v[90:93], v[168:171], v[208:211], v[90:93]
	v_mfma_f32_16x16x32_bf16 v[78:81], v[160:163], v[216:219], v[78:81]
	v_mfma_f32_16x16x32_bf16 v[74:77], v[168:171], v[216:219], v[74:77]
	v_mfma_f32_16x16x32_bf16 v[126:129], v[164:167], v[196:199], v[126:129]
	v_mfma_f32_16x16x32_bf16 v[122:125], v[172:175], v[196:199], v[122:125]
	v_mfma_f32_16x16x32_bf16 v[110:113], v[164:167], v[204:207], v[110:113]
	v_mfma_f32_16x16x32_bf16 v[106:109], v[172:175], v[204:207], v[106:109]
	v_mfma_f32_16x16x32_bf16 v[94:97], v[164:167], v[212:215], v[94:97]
	v_mfma_f32_16x16x32_bf16 v[90:93], v[172:175], v[212:215], v[90:93]
	v_mfma_f32_16x16x32_bf16 v[78:81], v[164:167], v[220:223], v[78:81]
	v_mfma_f32_16x16x32_bf16 v[74:77], v[172:175], v[220:223], v[74:77]
	v_mfma_f32_16x16x32_bf16 v[118:121], v[176:179], v[192:195], v[118:121]
	v_mfma_f32_16x16x32_bf16 v[114:117], v[184:187], v[192:195], v[114:117]
	v_mfma_f32_16x16x32_bf16 v[102:105], v[176:179], v[200:203], v[102:105]
	v_mfma_f32_16x16x32_bf16 v[98:101], v[184:187], v[200:203], v[98:101]
	v_mfma_f32_16x16x32_bf16 v[86:89], v[176:179], v[208:211], v[86:89]
	v_mfma_f32_16x16x32_bf16 v[82:85], v[184:187], v[208:211], v[82:85]
	v_mfma_f32_16x16x32_bf16 v[70:73], v[176:179], v[216:219], v[70:73]
	v_mfma_f32_16x16x32_bf16 v[66:69], v[184:187], v[216:219], v[66:69]
	v_mfma_f32_16x16x32_bf16 v[118:121], v[180:183], v[196:199], v[118:121]
	v_mfma_f32_16x16x32_bf16 v[114:117], v[188:191], v[196:199], v[114:117]
	v_mfma_f32_16x16x32_bf16 v[102:105], v[180:183], v[204:207], v[102:105]
	v_mfma_f32_16x16x32_bf16 v[98:101], v[188:191], v[204:207], v[98:101]
	v_mfma_f32_16x16x32_bf16 v[86:89], v[180:183], v[212:215], v[86:89]
	v_mfma_f32_16x16x32_bf16 v[82:85], v[188:191], v[212:215], v[82:85]
	v_mfma_f32_16x16x32_bf16 v[70:73], v[180:183], v[220:223], v[70:73]
	v_mfma_f32_16x16x32_bf16 v[66:69], v[188:191], v[220:223], v[66:69]
	s_setprio 1
	s_barrier
	s_add_i32 s72, s72, s35
	v_lshl_add_u64 v[140:141], s[70:71], 0, v[0:1]
	s_mov_b32 m0, s72
	ds_read_b128 v[192:195], v146 offset:16384
	ds_read_b128 v[196:199], v146 offset:17408
	ds_read_b128 v[200:203], v146 offset:18432
	ds_read_b128 v[204:207], v146 offset:19456
	ds_read_b128 v[208:211], v146 offset:20480
	ds_read_b128 v[212:215], v146 offset:21504
	ds_read_b128 v[216:219], v146 offset:22528
	ds_read_b128 v[220:223], v146 offset:23552
	global_load_lds_dwordx4 v[140:141], off
	s_add_i32 m0, s72, 0x2000
	v_lshl_add_u64 v[148:149], s[70:71], 0, v[134:135]
	s_add_u32 s70, s70, s80
	s_addc_u32 s71, s71, 0
	s_add_i32 s67, s67, s35
	global_load_lds_dwordx4 v[148:149], off
	v_lshl_add_u64 v[224:225], s[70:71], 0, v[0:1]
	s_mov_b32 m0, s67
	v_lshl_add_u64 v[226:227], s[70:71], 0, v[134:135]
	global_load_lds_dwordx4 v[224:225], off
	s_add_i32 m0, s67, 0x2000
	v_lshl_add_u64 v[228:229], s[20:21], 0, v[130:131]
	global_load_lds_dwordx4 v[226:227], off
	s_mov_b32 m0, s19
	v_lshl_add_u64 v[230:231], s[20:21], 0, v[132:133]
	global_load_lds_dwordx4 v[228:229], off
	s_mov_b32 m0, s29
	s_nop 0
	global_load_lds_dwordx4 v[230:231], off
	s_waitcnt vmcnt(8)
	s_waitcnt lgkmcnt(0)
	s_barrier
	s_setprio 0
	s_waitcnt lgkmcnt(0)
	v_mfma_f32_16x16x32_bf16 v[62:65], v[160:163], v[192:195], v[62:65]
	v_mfma_f32_16x16x32_bf16 v[58:61], v[168:171], v[192:195], v[58:61]
	v_mfma_f32_16x16x32_bf16 v[46:49], v[160:163], v[200:203], v[46:49]
	v_mfma_f32_16x16x32_bf16 v[42:45], v[168:171], v[200:203], v[42:45]
	v_mfma_f32_16x16x32_bf16 v[30:33], v[160:163], v[208:211], v[30:33]
	v_mfma_f32_16x16x32_bf16 v[26:29], v[168:171], v[208:211], v[26:29]
	v_mfma_f32_16x16x32_bf16 v[14:17], v[160:163], v[216:219], v[14:17]
	v_mfma_f32_16x16x32_bf16 v[10:13], v[168:171], v[216:219], v[10:13]
	v_mfma_f32_16x16x32_bf16 v[62:65], v[164:167], v[196:199], v[62:65]
	v_mfma_f32_16x16x32_bf16 v[58:61], v[172:175], v[196:199], v[58:61]
	v_mfma_f32_16x16x32_bf16 v[46:49], v[164:167], v[204:207], v[46:49]
	v_mfma_f32_16x16x32_bf16 v[42:45], v[172:175], v[204:207], v[42:45]
	v_mfma_f32_16x16x32_bf16 v[30:33], v[164:167], v[212:215], v[30:33]
	v_mfma_f32_16x16x32_bf16 v[26:29], v[172:175], v[212:215], v[26:29]
	v_mfma_f32_16x16x32_bf16 v[14:17], v[164:167], v[220:223], v[14:17]
	v_mfma_f32_16x16x32_bf16 v[10:13], v[172:175], v[220:223], v[10:13]
	v_mfma_f32_16x16x32_bf16 v[54:57], v[176:179], v[192:195], v[54:57]
	v_mfma_f32_16x16x32_bf16 v[50:53], v[184:187], v[192:195], v[50:53]
	v_mfma_f32_16x16x32_bf16 v[38:41], v[176:179], v[200:203], v[38:41]
	v_mfma_f32_16x16x32_bf16 v[34:37], v[184:187], v[200:203], v[34:37]
	v_mfma_f32_16x16x32_bf16 v[22:25], v[176:179], v[208:211], v[22:25]
	v_mfma_f32_16x16x32_bf16 v[18:21], v[184:187], v[208:211], v[18:21]
	v_mfma_f32_16x16x32_bf16 v[6:9], v[176:179], v[216:219], v[6:9]
	v_mfma_f32_16x16x32_bf16 v[2:5], v[184:187], v[216:219], v[2:5]
	v_mfma_f32_16x16x32_bf16 v[54:57], v[180:183], v[196:199], v[54:57]
	v_mfma_f32_16x16x32_bf16 v[50:53], v[188:191], v[196:199], v[50:53]
	v_mfma_f32_16x16x32_bf16 v[38:41], v[180:183], v[204:207], v[38:41]
	v_mfma_f32_16x16x32_bf16 v[34:37], v[188:191], v[204:207], v[34:37]
	v_mfma_f32_16x16x32_bf16 v[22:25], v[180:183], v[212:215], v[22:25]
	v_mfma_f32_16x16x32_bf16 v[18:21], v[188:191], v[212:215], v[18:21]
	v_mfma_f32_16x16x32_bf16 v[6:9], v[180:183], v[220:223], v[6:9]
	v_mfma_f32_16x16x32_bf16 v[2:5], v[188:191], v[220:223], v[2:5]
	s_setprio 1
	s_barrier
	s_add_i32 s67, 0, 0x18000
	v_add_u32_e32 v159, s67, v143
	s_add_i32 s70, 0, 0x1c000
	ds_read_b128 v[160:163], v159
	ds_read_b128 v[164:167], v159 offset:1024
	ds_read_b128 v[168:171], v159 offset:2048
	ds_read_b128 v[172:175], v159 offset:3072
	v_add_u32_e32 v159, s70, v143
	ds_read_b128 v[176:179], v159
	ds_read_b128 v[180:183], v159 offset:1024
	ds_read_b128 v[184:187], v159 offset:2048
	ds_read_b128 v[188:191], v159 offset:3072
	s_add_u32 s20, s20, s80
	s_addc_u32 s21, s21, 0
	s_mov_b32 m0, s30
	v_lshl_add_u64 v[232:233], s[20:21], 0, v[130:131]
	ds_read_b128 v[192:195], v146 offset:32768
	ds_read_b128 v[196:199], v146 offset:33792
	ds_read_b128 v[200:203], v146 offset:34816
	ds_read_b128 v[204:207], v146 offset:35840
	ds_read_b128 v[208:211], v146 offset:36864
	ds_read_b128 v[212:215], v146 offset:37888
	ds_read_b128 v[216:219], v146 offset:38912
	ds_read_b128 v[220:223], v146 offset:39936
	global_load_lds_dwordx4 v[232:233], off
	v_lshl_add_u64 v[232:233], s[20:21], 0, v[132:133]
	s_mov_b32 m0, s31
	s_nop 0
	global_load_lds_dwordx4 v[232:233], off
	s_waitcnt vmcnt(8)
	s_waitcnt lgkmcnt(0)
	s_barrier
	s_setprio 0
	s_waitcnt lgkmcnt(0)
	v_mfma_f32_16x16x32_bf16 v[126:129], v[160:163], v[192:195], v[126:129]
	v_mfma_f32_16x16x32_bf16 v[122:125], v[168:171], v[192:195], v[122:125]
	v_mfma_f32_16x16x32_bf16 v[110:113], v[160:163], v[200:203], v[110:113]
	v_mfma_f32_16x16x32_bf16 v[106:109], v[168:171], v[200:203], v[106:109]
	v_mfma_f32_16x16x32_bf16 v[94:97], v[160:163], v[208:211], v[94:97]
	v_mfma_f32_16x16x32_bf16 v[90:93], v[168:171], v[208:211], v[90:93]
	v_mfma_f32_16x16x32_bf16 v[78:81], v[160:163], v[216:219], v[78:81]
	v_mfma_f32_16x16x32_bf16 v[74:77], v[168:171], v[216:219], v[74:77]
	v_mfma_f32_16x16x32_bf16 v[126:129], v[164:167], v[196:199], v[126:129]
	v_mfma_f32_16x16x32_bf16 v[122:125], v[172:175], v[196:199], v[122:125]
	v_mfma_f32_16x16x32_bf16 v[110:113], v[164:167], v[204:207], v[110:113]
	v_mfma_f32_16x16x32_bf16 v[106:109], v[172:175], v[204:207], v[106:109]
	v_mfma_f32_16x16x32_bf16 v[94:97], v[164:167], v[212:215], v[94:97]
	v_mfma_f32_16x16x32_bf16 v[90:93], v[172:175], v[212:215], v[90:93]
	v_mfma_f32_16x16x32_bf16 v[78:81], v[164:167], v[220:223], v[78:81]
	v_mfma_f32_16x16x32_bf16 v[74:77], v[172:175], v[220:223], v[74:77]
	v_mfma_f32_16x16x32_bf16 v[118:121], v[176:179], v[192:195], v[118:121]
	v_mfma_f32_16x16x32_bf16 v[114:117], v[184:187], v[192:195], v[114:117]
	v_mfma_f32_16x16x32_bf16 v[102:105], v[176:179], v[200:203], v[102:105]
	v_mfma_f32_16x16x32_bf16 v[98:101], v[184:187], v[200:203], v[98:101]
	v_mfma_f32_16x16x32_bf16 v[86:89], v[176:179], v[208:211], v[86:89]
	v_mfma_f32_16x16x32_bf16 v[82:85], v[184:187], v[208:211], v[82:85]
	v_mfma_f32_16x16x32_bf16 v[70:73], v[176:179], v[216:219], v[70:73]
	v_mfma_f32_16x16x32_bf16 v[66:69], v[184:187], v[216:219], v[66:69]
	v_mfma_f32_16x16x32_bf16 v[118:121], v[180:183], v[196:199], v[118:121]
	v_mfma_f32_16x16x32_bf16 v[114:117], v[188:191], v[196:199], v[114:117]
	v_mfma_f32_16x16x32_bf16 v[102:105], v[180:183], v[204:207], v[102:105]
	v_mfma_f32_16x16x32_bf16 v[98:101], v[188:191], v[204:207], v[98:101]
	v_mfma_f32_16x16x32_bf16 v[86:89], v[180:183], v[212:215], v[86:89]
	v_mfma_f32_16x16x32_bf16 v[82:85], v[188:191], v[212:215], v[82:85]
	v_mfma_f32_16x16x32_bf16 v[70:73], v[180:183], v[220:223], v[70:73]
	v_mfma_f32_16x16x32_bf16 v[66:69], v[188:191], v[220:223], v[66:69]
	s_setprio 1
	s_barrier
	s_add_i32 s20, s67, s35
	v_lshl_add_u64 v[140:141], v[140:141], 0, s[94:95]
	s_mov_b32 m0, s20
	ds_read_b128 v[192:195], v146 offset:49152
	ds_read_b128 v[196:199], v146 offset:50176
	ds_read_b128 v[200:203], v146 offset:51200
	ds_read_b128 v[204:207], v146 offset:52224
	ds_read_b128 v[208:211], v146 offset:53248
	ds_read_b128 v[212:215], v146 offset:54272
	ds_read_b128 v[216:219], v146 offset:55296
	ds_read_b128 v[220:223], v146 offset:56320
	global_load_lds_dwordx4 v[140:141], off
	v_lshl_add_u64 v[140:141], v[148:149], 0, s[94:95]
	s_add_i32 m0, s20, 0x2000
	s_add_i32 s20, s70, s35
	global_load_lds_dwordx4 v[140:141], off
	v_lshl_add_u64 v[140:141], v[224:225], 0, s[94:95]
	s_mov_b32 m0, s20
	s_nop 0
	global_load_lds_dwordx4 v[140:141], off
	v_lshl_add_u64 v[140:141], v[226:227], 0, s[94:95]
	s_add_i32 m0, s20, 0x2000
	s_nop 0
	global_load_lds_dwordx4 v[140:141], off
	v_lshl_add_u64 v[140:141], v[228:229], 0, s[94:95]
	s_mov_b32 m0, s56
	s_nop 0
	global_load_lds_dwordx4 v[140:141], off
	v_lshl_add_u64 v[140:141], v[230:231], 0, s[94:95]
	s_mov_b32 m0, s57
	s_nop 0
	global_load_lds_dwordx4 v[140:141], off
	s_waitcnt vmcnt(8)
	s_waitcnt lgkmcnt(0)
	s_barrier
	s_setprio 0
	s_waitcnt lgkmcnt(0)
	v_mfma_f32_16x16x32_bf16 v[62:65], v[160:163], v[192:195], v[62:65]
	v_mfma_f32_16x16x32_bf16 v[58:61], v[168:171], v[192:195], v[58:61]
	v_mfma_f32_16x16x32_bf16 v[46:49], v[160:163], v[200:203], v[46:49]
	v_mfma_f32_16x16x32_bf16 v[42:45], v[168:171], v[200:203], v[42:45]
	v_mfma_f32_16x16x32_bf16 v[30:33], v[160:163], v[208:211], v[30:33]
	v_mfma_f32_16x16x32_bf16 v[26:29], v[168:171], v[208:211], v[26:29]
	v_mfma_f32_16x16x32_bf16 v[14:17], v[160:163], v[216:219], v[14:17]
	v_mfma_f32_16x16x32_bf16 v[10:13], v[168:171], v[216:219], v[10:13]
	v_mfma_f32_16x16x32_bf16 v[62:65], v[164:167], v[196:199], v[62:65]
	v_mfma_f32_16x16x32_bf16 v[58:61], v[172:175], v[196:199], v[58:61]
	v_mfma_f32_16x16x32_bf16 v[46:49], v[164:167], v[204:207], v[46:49]
	v_mfma_f32_16x16x32_bf16 v[42:45], v[172:175], v[204:207], v[42:45]
	v_mfma_f32_16x16x32_bf16 v[30:33], v[164:167], v[212:215], v[30:33]
	v_mfma_f32_16x16x32_bf16 v[26:29], v[172:175], v[212:215], v[26:29]
	v_mfma_f32_16x16x32_bf16 v[14:17], v[164:167], v[220:223], v[14:17]
	v_mfma_f32_16x16x32_bf16 v[10:13], v[172:175], v[220:223], v[10:13]
	v_mfma_f32_16x16x32_bf16 v[54:57], v[176:179], v[192:195], v[54:57]
	v_mfma_f32_16x16x32_bf16 v[50:53], v[184:187], v[192:195], v[50:53]
	v_mfma_f32_16x16x32_bf16 v[38:41], v[176:179], v[200:203], v[38:41]
	v_mfma_f32_16x16x32_bf16 v[34:37], v[184:187], v[200:203], v[34:37]
	v_mfma_f32_16x16x32_bf16 v[22:25], v[176:179], v[208:211], v[22:25]
	v_mfma_f32_16x16x32_bf16 v[18:21], v[184:187], v[208:211], v[18:21]
	v_mfma_f32_16x16x32_bf16 v[6:9], v[176:179], v[216:219], v[6:9]
	v_mfma_f32_16x16x32_bf16 v[2:5], v[184:187], v[216:219], v[2:5]
	v_mfma_f32_16x16x32_bf16 v[54:57], v[180:183], v[196:199], v[54:57]
	v_mfma_f32_16x16x32_bf16 v[50:53], v[188:191], v[196:199], v[50:53]
	v_mfma_f32_16x16x32_bf16 v[38:41], v[180:183], v[204:207], v[38:41]
	v_mfma_f32_16x16x32_bf16 v[34:37], v[188:191], v[204:207], v[34:37]
	v_mfma_f32_16x16x32_bf16 v[22:25], v[180:183], v[212:215], v[22:25]
	v_mfma_f32_16x16x32_bf16 v[18:21], v[188:191], v[212:215], v[18:21]
	v_mfma_f32_16x16x32_bf16 v[6:9], v[180:183], v[220:223], v[6:9]
	v_mfma_f32_16x16x32_bf16 v[2:5], v[188:191], v[220:223], v[2:5]
	s_setprio 1
	s_barrier
	s_add_u32 s16, s16, 0x100
	s_addc_u32 s17, s17, 0
	s_add_u32 s64, s64, 0x100
	s_addc_u32 s65, s65, 0
	s_cmp_ge_u32 s66, s55
	s_mov_b32 s20, s66
	s_cbranch_scc0 .LBB0_334
	s_and_b64 vcc, exec, s[10:11]
	s_cbranch_vccz .LBB0_337
	s_barrier

.LBB0_360:
	s_add_i32 s30, s10, 2
	s_add_u32 s31, s2, 0x80
	s_addc_u32 s11, s3, 0
	s_add_i32 s35, 0, 0x10000
	s_cmp_eq_u32 s58, s10
	s_cselect_b32 s11, s1, s11
	s_cselect_b32 s10, s0, s31
	v_add_u32_e32 v148, s35, v160
	s_cselect_b32 s67, s7, s29
	s_cselect_b32 s66, s6, s19
	s_add_i32 s31, 0, 0x14000
	ds_read_b128 v[140:143], v148
	ds_read_b128 v[144:147], v148 offset:1024
	ds_read_b128 v[180:183], v148 offset:2048
	ds_read_b128 v[184:187], v148 offset:3072
	v_add_u32_e32 v148, s31, v160
	ds_read_b128 v[188:191], v148
	ds_read_b128 v[192:195], v148 offset:1024
	ds_read_b128 v[196:199], v148 offset:2048
	ds_read_b128 v[200:203], v148 offset:3072
	v_lshl_add_u64 v[148:149], s[2:3], 0, v[136:137]
	s_add_i32 m0, s23, 0xc000
	ds_read_b128 v[204:207], v172
	ds_read_b128 v[208:211], v172 offset:1024
	ds_read_b128 v[212:215], v172 offset:2048
	ds_read_b128 v[216:219], v172 offset:3072
	ds_read_b128 v[220:223], v172 offset:4096
	ds_read_b128 v[224:227], v172 offset:5120
	ds_read_b128 v[228:231], v172 offset:6144
	ds_read_b128 v[232:235], v172 offset:7168
	global_load_lds_dwordx4 v[148:149], off
	v_lshl_add_u64 v[148:149], s[2:3], 0, v[138:139]
	s_add_i32 m0, s23, 0xe000
	s_nop 0
	global_load_lds_dwordx4 v[148:149], off
	s_waitcnt vmcnt(8)
	s_waitcnt lgkmcnt(0)
	s_barrier
	s_setprio 0
	s_waitcnt lgkmcnt(0)
	v_mfma_f32_16x16x32_bf16 v[126:129], v[140:143], v[204:207], v[126:129]
	v_mfma_f32_16x16x32_bf16 v[122:125], v[180:183], v[204:207], v[122:125]
	v_mfma_f32_16x16x32_bf16 v[110:113], v[140:143], v[212:215], v[110:113]
	v_mfma_f32_16x16x32_bf16 v[106:109], v[180:183], v[212:215], v[106:109]
	v_mfma_f32_16x16x32_bf16 v[94:97], v[140:143], v[220:223], v[94:97]
	v_mfma_f32_16x16x32_bf16 v[90:93], v[180:183], v[220:223], v[90:93]
	v_mfma_f32_16x16x32_bf16 v[78:81], v[140:143], v[228:231], v[78:81]
	v_mfma_f32_16x16x32_bf16 v[74:77], v[180:183], v[228:231], v[74:77]
	v_mfma_f32_16x16x32_bf16 v[126:129], v[144:147], v[208:211], v[126:129]
	v_mfma_f32_16x16x32_bf16 v[122:125], v[184:187], v[208:211], v[122:125]
	v_mfma_f32_16x16x32_bf16 v[110:113], v[144:147], v[216:219], v[110:113]
	v_mfma_f32_16x16x32_bf16 v[106:109], v[184:187], v[216:219], v[106:109]
	v_mfma_f32_16x16x32_bf16 v[94:97], v[144:147], v[224:227], v[94:97]
	v_mfma_f32_16x16x32_bf16 v[90:93], v[184:187], v[224:227], v[90:93]
	v_mfma_f32_16x16x32_bf16 v[78:81], v[144:147], v[232:235], v[78:81]
	v_mfma_f32_16x16x32_bf16 v[74:77], v[184:187], v[232:235], v[74:77]
	v_mfma_f32_16x16x32_bf16 v[118:121], v[188:191], v[204:207], v[118:121]
	v_mfma_f32_16x16x32_bf16 v[114:117], v[196:199], v[204:207], v[114:117]
	v_mfma_f32_16x16x32_bf16 v[102:105], v[188:191], v[212:215], v[102:105]
	v_mfma_f32_16x16x32_bf16 v[98:101], v[196:199], v[212:215], v[98:101]
	v_mfma_f32_16x16x32_bf16 v[86:89], v[188:191], v[220:223], v[86:89]
	v_mfma_f32_16x16x32_bf16 v[82:85], v[196:199], v[220:223], v[82:85]
	v_mfma_f32_16x16x32_bf16 v[70:73], v[188:191], v[228:231], v[70:73]
	v_mfma_f32_16x16x32_bf16 v[66:69], v[196:199], v[228:231], v[66:69]
	v_mfma_f32_16x16x32_bf16 v[118:121], v[192:195], v[208:211], v[118:121]
	v_mfma_f32_16x16x32_bf16 v[114:117], v[200:203], v[208:211], v[114:117]
	v_mfma_f32_16x16x32_bf16 v[102:105], v[192:195], v[216:219], v[102:105]
	v_mfma_f32_16x16x32_bf16 v[98:101], v[200:203], v[216:219], v[98:101]
	v_mfma_f32_16x16x32_bf16 v[86:89], v[192:195], v[224:227], v[86:89]
	v_mfma_f32_16x16x32_bf16 v[82:85], v[200:203], v[224:227], v[82:85]
	v_mfma_f32_16x16x32_bf16 v[70:73], v[192:195], v[232:235], v[70:73]
	v_mfma_f32_16x16x32_bf16 v[66:69], v[200:203], v[232:235], v[66:69]
	s_setprio 1
	s_barrier
	s_add_i32 s35, s35, s20
	v_lshl_add_u64 v[148:149], s[66:67], 0, v[0:1]
	s_mov_b32 m0, s35
	ds_read_b128 v[204:207], v172 offset:16384
	ds_read_b128 v[208:211], v172 offset:17408
	ds_read_b128 v[212:215], v172 offset:18432
	ds_read_b128 v[216:219], v172 offset:19456
	ds_read_b128 v[220:223], v172 offset:20480
	ds_read_b128 v[224:227], v172 offset:21504
	ds_read_b128 v[228:231], v172 offset:22528
	ds_read_b128 v[232:235], v172 offset:23552
	global_load_lds_dwordx4 v[148:149], off
	s_add_i32 m0, s35, 0x2000
	v_lshl_add_u64 v[236:237], s[66:67], 0, v[134:135]
	s_add_u32 s66, s66, s16
	s_addc_u32 s67, s67, 0
	s_add_i32 s31, s31, s20
	global_load_lds_dwordx4 v[236:237], off
	v_lshl_add_u64 v[238:239], s[66:67], 0, v[0:1]
	s_mov_b32 m0, s31
	v_lshl_add_u64 v[240:241], s[66:67], 0, v[134:135]
	global_load_lds_dwordx4 v[238:239], off
	s_add_i32 m0, s31, 0x2000
	v_lshl_add_u64 v[242:243], s[10:11], 0, v[130:131]
	global_load_lds_dwordx4 v[240:241], off
	s_mov_b32 m0, s23
	v_lshl_add_u64 v[244:245], s[10:11], 0, v[132:133]
	global_load_lds_dwordx4 v[242:243], off
	s_mov_b32 m0, s52
	s_nop 0
	global_load_lds_dwordx4 v[244:245], off
	s_waitcnt vmcnt(8)
	s_waitcnt lgkmcnt(0)
	s_barrier
	s_setprio 0
	s_waitcnt lgkmcnt(0)
	v_mfma_f32_16x16x32_bf16 v[62:65], v[140:143], v[204:207], v[62:65]
	v_mfma_f32_16x16x32_bf16 v[58:61], v[180:183], v[204:207], v[58:61]
	v_mfma_f32_16x16x32_bf16 v[46:49], v[140:143], v[212:215], v[46:49]
	v_mfma_f32_16x16x32_bf16 v[42:45], v[180:183], v[212:215], v[42:45]
	v_mfma_f32_16x16x32_bf16 v[30:33], v[140:143], v[220:223], v[30:33]
	v_mfma_f32_16x16x32_bf16 v[26:29], v[180:183], v[220:223], v[26:29]
	v_mfma_f32_16x16x32_bf16 v[14:17], v[140:143], v[228:231], v[14:17]
	v_mfma_f32_16x16x32_bf16 v[10:13], v[180:183], v[228:231], v[10:13]
	v_mfma_f32_16x16x32_bf16 v[62:65], v[144:147], v[208:211], v[62:65]
	v_mfma_f32_16x16x32_bf16 v[58:61], v[184:187], v[208:211], v[58:61]
	v_mfma_f32_16x16x32_bf16 v[46:49], v[144:147], v[216:219], v[46:49]
	v_mfma_f32_16x16x32_bf16 v[42:45], v[184:187], v[216:219], v[42:45]
	v_mfma_f32_16x16x32_bf16 v[30:33], v[144:147], v[224:227], v[30:33]
	v_mfma_f32_16x16x32_bf16 v[26:29], v[184:187], v[224:227], v[26:29]
	v_mfma_f32_16x16x32_bf16 v[14:17], v[144:147], v[232:235], v[14:17]
	v_mfma_f32_16x16x32_bf16 v[10:13], v[184:187], v[232:235], v[10:13]
	v_mfma_f32_16x16x32_bf16 v[54:57], v[188:191], v[204:207], v[54:57]
	v_mfma_f32_16x16x32_bf16 v[50:53], v[196:199], v[204:207], v[50:53]
	v_mfma_f32_16x16x32_bf16 v[38:41], v[188:191], v[212:215], v[38:41]
	v_mfma_f32_16x16x32_bf16 v[34:37], v[196:199], v[212:215], v[34:37]
	v_mfma_f32_16x16x32_bf16 v[22:25], v[188:191], v[220:223], v[22:25]
	v_mfma_f32_16x16x32_bf16 v[18:21], v[196:199], v[220:223], v[18:21]
	v_mfma_f32_16x16x32_bf16 v[6:9], v[188:191], v[228:231], v[6:9]
	v_mfma_f32_16x16x32_bf16 v[2:5], v[196:199], v[228:231], v[2:5]
	v_mfma_f32_16x16x32_bf16 v[54:57], v[192:195], v[208:211], v[54:57]
	v_mfma_f32_16x16x32_bf16 v[50:53], v[200:203], v[208:211], v[50:53]
	v_mfma_f32_16x16x32_bf16 v[38:41], v[192:195], v[216:219], v[38:41]
	v_mfma_f32_16x16x32_bf16 v[34:37], v[200:203], v[216:219], v[34:37]
	v_mfma_f32_16x16x32_bf16 v[22:25], v[192:195], v[224:227], v[22:25]
	v_mfma_f32_16x16x32_bf16 v[18:21], v[200:203], v[224:227], v[18:21]
	v_mfma_f32_16x16x32_bf16 v[6:9], v[192:195], v[232:235], v[6:9]
	v_mfma_f32_16x16x32_bf16 v[2:5], v[200:203], v[232:235], v[2:5]
	s_setprio 1
	s_barrier
	s_add_i32 s31, 0, 0x18000
	s_add_i32 s35, 0, 0x1c000
	v_add_u32_e32 v184, s31, v160
	v_add_u32_e32 v200, s35, v160
	ds_read_b128 v[140:143], v184
	ds_read_b128 v[144:147], v184 offset:1024
	ds_read_b128 v[180:183], v184 offset:2048
	ds_read_b128 v[184:187], v184 offset:3072
	ds_read_b128 v[188:191], v200
	ds_read_b128 v[192:195], v200 offset:1024
	ds_read_b128 v[196:199], v200 offset:2048
	ds_read_b128 v[200:203], v200 offset:3072
	s_add_u32 s10, s10, s16
	s_addc_u32 s11, s11, 0
	s_mov_b32 m0, s53
	v_lshl_add_u64 v[246:247], s[10:11], 0, v[130:131]
	ds_read_b128 v[204:207], v172 offset:32768
	ds_read_b128 v[208:211], v172 offset:33792
	ds_read_b128 v[212:215], v172 offset:34816
	ds_read_b128 v[216:219], v172 offset:35840
	ds_read_b128 v[220:223], v172 offset:36864
	ds_read_b128 v[224:227], v172 offset:37888
	ds_read_b128 v[228:231], v172 offset:38912
	ds_read_b128 v[232:235], v172 offset:39936
	global_load_lds_dwordx4 v[246:247], off
	v_lshl_add_u64 v[246:247], s[10:11], 0, v[132:133]
	s_mov_b32 m0, s54
	s_nop 0
	global_load_lds_dwordx4 v[246:247], off
	s_waitcnt vmcnt(8)
	s_waitcnt lgkmcnt(0)
	s_barrier
	s_setprio 0
	s_waitcnt lgkmcnt(0)
	v_mfma_f32_16x16x32_bf16 v[126:129], v[140:143], v[204:207], v[126:129]
	v_mfma_f32_16x16x32_bf16 v[122:125], v[180:183], v[204:207], v[122:125]
	v_mfma_f32_16x16x32_bf16 v[110:113], v[140:143], v[212:215], v[110:113]
	v_mfma_f32_16x16x32_bf16 v[106:109], v[180:183], v[212:215], v[106:109]
	v_mfma_f32_16x16x32_bf16 v[94:97], v[140:143], v[220:223], v[94:97]
	v_mfma_f32_16x16x32_bf16 v[90:93], v[180:183], v[220:223], v[90:93]
	v_mfma_f32_16x16x32_bf16 v[78:81], v[140:143], v[228:231], v[78:81]
	v_mfma_f32_16x16x32_bf16 v[74:77], v[180:183], v[228:231], v[74:77]
	v_mfma_f32_16x16x32_bf16 v[126:129], v[144:147], v[208:211], v[126:129]
	v_mfma_f32_16x16x32_bf16 v[122:125], v[184:187], v[208:211], v[122:125]
	v_mfma_f32_16x16x32_bf16 v[110:113], v[144:147], v[216:219], v[110:113]
	v_mfma_f32_16x16x32_bf16 v[106:109], v[184:187], v[216:219], v[106:109]
	v_mfma_f32_16x16x32_bf16 v[94:97], v[144:147], v[224:227], v[94:97]
	v_mfma_f32_16x16x32_bf16 v[90:93], v[184:187], v[224:227], v[90:93]
	v_mfma_f32_16x16x32_bf16 v[78:81], v[144:147], v[232:235], v[78:81]
	v_mfma_f32_16x16x32_bf16 v[74:77], v[184:187], v[232:235], v[74:77]
	v_mfma_f32_16x16x32_bf16 v[118:121], v[188:191], v[204:207], v[118:121]
	v_mfma_f32_16x16x32_bf16 v[114:117], v[196:199], v[204:207], v[114:117]
	v_mfma_f32_16x16x32_bf16 v[102:105], v[188:191], v[212:215], v[102:105]
	v_mfma_f32_16x16x32_bf16 v[98:101], v[196:199], v[212:215], v[98:101]
	v_mfma_f32_16x16x32_bf16 v[86:89], v[188:191], v[220:223], v[86:89]
	v_mfma_f32_16x16x32_bf16 v[82:85], v[196:199], v[220:223], v[82:85]
	v_mfma_f32_16x16x32_bf16 v[70:73], v[188:191], v[228:231], v[70:73]
	v_mfma_f32_16x16x32_bf16 v[66:69], v[196:199], v[228:231], v[66:69]
	v_mfma_f32_16x16x32_bf16 v[118:121], v[192:195], v[208:211], v[118:121]
	v_mfma_f32_16x16x32_bf16 v[114:117], v[200:203], v[208:211], v[114:117]
	v_mfma_f32_16x16x32_bf16 v[102:105], v[192:195], v[216:219], v[102:105]
	v_mfma_f32_16x16x32_bf16 v[98:101], v[200:203], v[216:219], v[98:101]
	v_mfma_f32_16x16x32_bf16 v[86:89], v[192:195], v[224:227], v[86:89]
	v_mfma_f32_16x16x32_bf16 v[82:85], v[200:203], v[224:227], v[82:85]
	v_mfma_f32_16x16x32_bf16 v[70:73], v[192:195], v[232:235], v[70:73]
	v_mfma_f32_16x16x32_bf16 v[66:69], v[200:203], v[232:235], v[66:69]
	s_setprio 1
	s_barrier
	s_add_i32 s10, s31, s20
	v_lshl_add_u64 v[148:149], v[148:149], 0, s[94:95]
	s_mov_b32 m0, s10
	ds_read_b128 v[204:207], v172 offset:49152
	ds_read_b128 v[208:211], v172 offset:50176
	ds_read_b128 v[212:215], v172 offset:51200
	ds_read_b128 v[216:219], v172 offset:52224
	ds_read_b128 v[220:223], v172 offset:53248
	ds_read_b128 v[224:227], v172 offset:54272
	ds_read_b128 v[228:231], v172 offset:55296
	ds_read_b128 v[232:235], v172 offset:56320
	global_load_lds_dwordx4 v[148:149], off
	v_lshl_add_u64 v[148:149], v[236:237], 0, s[94:95]
	s_add_i32 m0, s10, 0x2000
	s_add_i32 s10, s35, s20
	global_load_lds_dwordx4 v[148:149], off
	v_lshl_add_u64 v[148:149], v[238:239], 0, s[94:95]
	s_mov_b32 m0, s10
	s_nop 0
	global_load_lds_dwordx4 v[148:149], off
	v_lshl_add_u64 v[148:149], v[240:241], 0, s[94:95]
	s_add_i32 m0, s10, 0x2000
	s_nop 0
	global_load_lds_dwordx4 v[148:149], off
	v_lshl_add_u64 v[148:149], v[242:243], 0, s[94:95]
	s_mov_b32 m0, s56
	s_nop 0
	global_load_lds_dwordx4 v[148:149], off
	v_lshl_add_u64 v[148:149], v[244:245], 0, s[94:95]
	s_mov_b32 m0, s57
	s_nop 0
	global_load_lds_dwordx4 v[148:149], off
	s_waitcnt vmcnt(8)
	s_waitcnt lgkmcnt(0)
	s_barrier
	s_setprio 0
	s_waitcnt lgkmcnt(0)
	v_mfma_f32_16x16x32_bf16 v[62:65], v[140:143], v[204:207], v[62:65]
	v_mfma_f32_16x16x32_bf16 v[58:61], v[180:183], v[204:207], v[58:61]
	v_mfma_f32_16x16x32_bf16 v[46:49], v[140:143], v[212:215], v[46:49]
	v_mfma_f32_16x16x32_bf16 v[42:45], v[180:183], v[212:215], v[42:45]
	v_mfma_f32_16x16x32_bf16 v[30:33], v[140:143], v[220:223], v[30:33]
	v_mfma_f32_16x16x32_bf16 v[26:29], v[180:183], v[220:223], v[26:29]
	v_mfma_f32_16x16x32_bf16 v[14:17], v[140:143], v[228:231], v[14:17]
	v_mfma_f32_16x16x32_bf16 v[10:13], v[180:183], v[228:231], v[10:13]
	v_mfma_f32_16x16x32_bf16 v[62:65], v[144:147], v[208:211], v[62:65]
	v_mfma_f32_16x16x32_bf16 v[58:61], v[184:187], v[208:211], v[58:61]
	v_mfma_f32_16x16x32_bf16 v[46:49], v[144:147], v[216:219], v[46:49]
	v_mfma_f32_16x16x32_bf16 v[42:45], v[184:187], v[216:219], v[42:45]
	v_mfma_f32_16x16x32_bf16 v[30:33], v[144:147], v[224:227], v[30:33]
	v_mfma_f32_16x16x32_bf16 v[26:29], v[184:187], v[224:227], v[26:29]
	v_mfma_f32_16x16x32_bf16 v[14:17], v[144:147], v[232:235], v[14:17]
	v_mfma_f32_16x16x32_bf16 v[10:13], v[184:187], v[232:235], v[10:13]
	v_mfma_f32_16x16x32_bf16 v[54:57], v[188:191], v[204:207], v[54:57]
	v_mfma_f32_16x16x32_bf16 v[50:53], v[196:199], v[204:207], v[50:53]
	v_mfma_f32_16x16x32_bf16 v[38:41], v[188:191], v[212:215], v[38:41]
	v_mfma_f32_16x16x32_bf16 v[34:37], v[196:199], v[212:215], v[34:37]
	v_mfma_f32_16x16x32_bf16 v[22:25], v[188:191], v[220:223], v[22:25]
	v_mfma_f32_16x16x32_bf16 v[18:21], v[196:199], v[220:223], v[18:21]
	v_mfma_f32_16x16x32_bf16 v[6:9], v[188:191], v[228:231], v[6:9]
	v_mfma_f32_16x16x32_bf16 v[2:5], v[196:199], v[228:231], v[2:5]
	v_mfma_f32_16x16x32_bf16 v[54:57], v[192:195], v[208:211], v[54:57]
	v_mfma_f32_16x16x32_bf16 v[50:53], v[200:203], v[208:211], v[50:53]
	v_mfma_f32_16x16x32_bf16 v[38:41], v[192:195], v[216:219], v[38:41]
	v_mfma_f32_16x16x32_bf16 v[34:37], v[200:203], v[216:219], v[34:37]
	v_mfma_f32_16x16x32_bf16 v[22:25], v[192:195], v[224:227], v[22:25]
	v_mfma_f32_16x16x32_bf16 v[18:21], v[200:203], v[224:227], v[18:21]
	v_mfma_f32_16x16x32_bf16 v[6:9], v[192:195], v[232:235], v[6:9]
	v_mfma_f32_16x16x32_bf16 v[2:5], v[200:203], v[232:235], v[2:5]
	s_setprio 1
	s_barrier
	s_add_u32 s2, s2, 0x100
	s_addc_u32 s3, s3, 0
	s_add_u32 s19, s19, 0x100
	s_addc_u32 s29, s29, 0
	s_cmp_ge_u32 s30, s55
	s_mov_b32 s10, s30
	s_cbranch_scc0 .LBB0_360
	s_and_b64 vcc, exec, s[14:15]
	s_cbranch_vccz .LBB0_363
	s_barrier

.LBB0_419:
	s_add_i32 s66, s20, 2
	s_add_u32 s67, s16, 0x80
	s_addc_u32 s21, s17, 0
	s_add_i32 s72, 0, 0x10000
	s_cmp_eq_u32 s58, s20
	s_cselect_b32 s21, s1, s21
	s_cselect_b32 s20, s0, s67
	v_add_u32_e32 v140, s72, v143
	s_cselect_b32 s71, s15, s65
	s_cselect_b32 s70, s14, s64
	s_add_i32 s67, 0, 0x14000
	ds_read_b128 v[160:163], v140
	ds_read_b128 v[164:167], v140 offset:1024
	ds_read_b128 v[168:171], v140 offset:2048
	ds_read_b128 v[172:175], v140 offset:3072
	v_add_u32_e32 v140, s67, v143
	ds_read_b128 v[176:179], v140
	ds_read_b128 v[180:183], v140 offset:1024
	ds_read_b128 v[184:187], v140 offset:2048
	ds_read_b128 v[188:191], v140 offset:3072
	v_lshl_add_u64 v[140:141], s[16:17], 0, v[136:137]
	s_add_i32 m0, s35, 0xc000
	ds_read_b128 v[192:195], v146
	ds_read_b128 v[196:199], v146 offset:1024
	ds_read_b128 v[200:203], v146 offset:2048
	ds_read_b128 v[204:207], v146 offset:3072
	ds_read_b128 v[208:211], v146 offset:4096
	ds_read_b128 v[212:215], v146 offset:5120
	ds_read_b128 v[216:219], v146 offset:6144
	ds_read_b128 v[220:223], v146 offset:7168
	global_load_lds_dwordx4 v[140:141], off
	v_lshl_add_u64 v[140:141], s[16:17], 0, v[138:139]
	s_add_i32 m0, s35, 0xe000
	s_nop 0
	global_load_lds_dwordx4 v[140:141], off
	s_waitcnt vmcnt(8)
	s_waitcnt lgkmcnt(0)
	s_barrier
	s_setprio 0
	s_waitcnt lgkmcnt(0)
	v_mfma_f32_16x16x32_bf16 v[126:129], v[160:163], v[192:195], v[126:129]
	v_mfma_f32_16x16x32_bf16 v[122:125], v[168:171], v[192:195], v[122:125]
	v_mfma_f32_16x16x32_bf16 v[110:113], v[160:163], v[200:203], v[110:113]
	v_mfma_f32_16x16x32_bf16 v[106:109], v[168:171], v[200:203], v[106:109]
	v_mfma_f32_16x16x32_bf16 v[94:97], v[160:163], v[208:211], v[94:97]
	v_mfma_f32_16x16x32_bf16 v[90:93], v[168:171], v[208:211], v[90:93]
	v_mfma_f32_16x16x32_bf16 v[78:81], v[160:163], v[216:219], v[78:81]
	v_mfma_f32_16x16x32_bf16 v[74:77], v[168:171], v[216:219], v[74:77]
	v_mfma_f32_16x16x32_bf16 v[126:129], v[164:167], v[196:199], v[126:129]
	v_mfma_f32_16x16x32_bf16 v[122:125], v[172:175], v[196:199], v[122:125]
	v_mfma_f32_16x16x32_bf16 v[110:113], v[164:167], v[204:207], v[110:113]
	v_mfma_f32_16x16x32_bf16 v[106:109], v[172:175], v[204:207], v[106:109]
	v_mfma_f32_16x16x32_bf16 v[94:97], v[164:167], v[212:215], v[94:97]
	v_mfma_f32_16x16x32_bf16 v[90:93], v[172:175], v[212:215], v[90:93]
	v_mfma_f32_16x16x32_bf16 v[78:81], v[164:167], v[220:223], v[78:81]
	v_mfma_f32_16x16x32_bf16 v[74:77], v[172:175], v[220:223], v[74:77]
	v_mfma_f32_16x16x32_bf16 v[118:121], v[176:179], v[192:195], v[118:121]
	v_mfma_f32_16x16x32_bf16 v[114:117], v[184:187], v[192:195], v[114:117]
	v_mfma_f32_16x16x32_bf16 v[102:105], v[176:179], v[200:203], v[102:105]
	v_mfma_f32_16x16x32_bf16 v[98:101], v[184:187], v[200:203], v[98:101]
	v_mfma_f32_16x16x32_bf16 v[86:89], v[176:179], v[208:211], v[86:89]
	v_mfma_f32_16x16x32_bf16 v[82:85], v[184:187], v[208:211], v[82:85]
	v_mfma_f32_16x16x32_bf16 v[70:73], v[176:179], v[216:219], v[70:73]
	v_mfma_f32_16x16x32_bf16 v[66:69], v[184:187], v[216:219], v[66:69]
	v_mfma_f32_16x16x32_bf16 v[118:121], v[180:183], v[196:199], v[118:121]
	v_mfma_f32_16x16x32_bf16 v[114:117], v[188:191], v[196:199], v[114:117]
	v_mfma_f32_16x16x32_bf16 v[102:105], v[180:183], v[204:207], v[102:105]
	v_mfma_f32_16x16x32_bf16 v[98:101], v[188:191], v[204:207], v[98:101]
	v_mfma_f32_16x16x32_bf16 v[86:89], v[180:183], v[212:215], v[86:89]
	v_mfma_f32_16x16x32_bf16 v[82:85], v[188:191], v[212:215], v[82:85]
	v_mfma_f32_16x16x32_bf16 v[70:73], v[180:183], v[220:223], v[70:73]
	v_mfma_f32_16x16x32_bf16 v[66:69], v[188:191], v[220:223], v[66:69]
	s_setprio 1
	s_barrier
	s_add_i32 s72, s72, s30
	v_lshl_add_u64 v[140:141], s[70:71], 0, v[0:1]
	s_mov_b32 m0, s72
	ds_read_b128 v[192:195], v146 offset:16384
	ds_read_b128 v[196:199], v146 offset:17408
	ds_read_b128 v[200:203], v146 offset:18432
	ds_read_b128 v[204:207], v146 offset:19456
	ds_read_b128 v[208:211], v146 offset:20480
	ds_read_b128 v[212:215], v146 offset:21504
	ds_read_b128 v[216:219], v146 offset:22528
	ds_read_b128 v[220:223], v146 offset:23552
	global_load_lds_dwordx4 v[140:141], off
	s_add_i32 m0, s72, 0x2000
	v_lshl_add_u64 v[148:149], s[70:71], 0, v[134:135]
	s_add_u32 s70, s70, s80
	s_addc_u32 s71, s71, 0
	s_add_i32 s67, s67, s30
	global_load_lds_dwordx4 v[148:149], off
	v_lshl_add_u64 v[224:225], s[70:71], 0, v[0:1]
	s_mov_b32 m0, s67
	v_lshl_add_u64 v[226:227], s[70:71], 0, v[134:135]
	global_load_lds_dwordx4 v[224:225], off
	s_add_i32 m0, s67, 0x2000
	v_lshl_add_u64 v[228:229], s[20:21], 0, v[130:131]
	global_load_lds_dwordx4 v[226:227], off
	s_mov_b32 m0, s35
	v_lshl_add_u64 v[230:231], s[20:21], 0, v[132:133]
	global_load_lds_dwordx4 v[228:229], off
	s_mov_b32 m0, s52
	s_nop 0
	global_load_lds_dwordx4 v[230:231], off
	s_waitcnt vmcnt(8)
	s_waitcnt lgkmcnt(0)
	s_barrier
	s_setprio 0
	s_waitcnt lgkmcnt(0)
	v_mfma_f32_16x16x32_bf16 v[62:65], v[160:163], v[192:195], v[62:65]
	v_mfma_f32_16x16x32_bf16 v[58:61], v[168:171], v[192:195], v[58:61]
	v_mfma_f32_16x16x32_bf16 v[46:49], v[160:163], v[200:203], v[46:49]
	v_mfma_f32_16x16x32_bf16 v[42:45], v[168:171], v[200:203], v[42:45]
	v_mfma_f32_16x16x32_bf16 v[30:33], v[160:163], v[208:211], v[30:33]
	v_mfma_f32_16x16x32_bf16 v[26:29], v[168:171], v[208:211], v[26:29]
	v_mfma_f32_16x16x32_bf16 v[14:17], v[160:163], v[216:219], v[14:17]
	v_mfma_f32_16x16x32_bf16 v[10:13], v[168:171], v[216:219], v[10:13]
	v_mfma_f32_16x16x32_bf16 v[62:65], v[164:167], v[196:199], v[62:65]
	v_mfma_f32_16x16x32_bf16 v[58:61], v[172:175], v[196:199], v[58:61]
	v_mfma_f32_16x16x32_bf16 v[46:49], v[164:167], v[204:207], v[46:49]
	v_mfma_f32_16x16x32_bf16 v[42:45], v[172:175], v[204:207], v[42:45]
	v_mfma_f32_16x16x32_bf16 v[30:33], v[164:167], v[212:215], v[30:33]
	v_mfma_f32_16x16x32_bf16 v[26:29], v[172:175], v[212:215], v[26:29]
	v_mfma_f32_16x16x32_bf16 v[14:17], v[164:167], v[220:223], v[14:17]
	v_mfma_f32_16x16x32_bf16 v[10:13], v[172:175], v[220:223], v[10:13]
	v_mfma_f32_16x16x32_bf16 v[54:57], v[176:179], v[192:195], v[54:57]
	v_mfma_f32_16x16x32_bf16 v[50:53], v[184:187], v[192:195], v[50:53]
	v_mfma_f32_16x16x32_bf16 v[38:41], v[176:179], v[200:203], v[38:41]
	v_mfma_f32_16x16x32_bf16 v[34:37], v[184:187], v[200:203], v[34:37]
	v_mfma_f32_16x16x32_bf16 v[22:25], v[176:179], v[208:211], v[22:25]
	v_mfma_f32_16x16x32_bf16 v[18:21], v[184:187], v[208:211], v[18:21]
	v_mfma_f32_16x16x32_bf16 v[6:9], v[176:179], v[216:219], v[6:9]
	v_mfma_f32_16x16x32_bf16 v[2:5], v[184:187], v[216:219], v[2:5]
	v_mfma_f32_16x16x32_bf16 v[54:57], v[180:183], v[196:199], v[54:57]
	v_mfma_f32_16x16x32_bf16 v[50:53], v[188:191], v[196:199], v[50:53]
	v_mfma_f32_16x16x32_bf16 v[38:41], v[180:183], v[204:207], v[38:41]
	v_mfma_f32_16x16x32_bf16 v[34:37], v[188:191], v[204:207], v[34:37]
	v_mfma_f32_16x16x32_bf16 v[22:25], v[180:183], v[212:215], v[22:25]
	v_mfma_f32_16x16x32_bf16 v[18:21], v[188:191], v[212:215], v[18:21]
	v_mfma_f32_16x16x32_bf16 v[6:9], v[180:183], v[220:223], v[6:9]
	v_mfma_f32_16x16x32_bf16 v[2:5], v[188:191], v[220:223], v[2:5]
	s_setprio 1
	s_barrier
	s_add_i32 s67, 0, 0x18000
	v_add_u32_e32 v159, s67, v143
	s_add_i32 s70, 0, 0x1c000
	ds_read_b128 v[160:163], v159
	ds_read_b128 v[164:167], v159 offset:1024
	ds_read_b128 v[168:171], v159 offset:2048
	ds_read_b128 v[172:175], v159 offset:3072
	v_add_u32_e32 v159, s70, v143
	ds_read_b128 v[176:179], v159
	ds_read_b128 v[180:183], v159 offset:1024
	ds_read_b128 v[184:187], v159 offset:2048
	ds_read_b128 v[188:191], v159 offset:3072
	s_add_u32 s20, s20, s80
	s_addc_u32 s21, s21, 0
	s_mov_b32 m0, s53
	v_lshl_add_u64 v[232:233], s[20:21], 0, v[130:131]
	ds_read_b128 v[192:195], v146 offset:32768
	ds_read_b128 v[196:199], v146 offset:33792
	ds_read_b128 v[200:203], v146 offset:34816
	ds_read_b128 v[204:207], v146 offset:35840
	ds_read_b128 v[208:211], v146 offset:36864
	ds_read_b128 v[212:215], v146 offset:37888
	ds_read_b128 v[216:219], v146 offset:38912
	ds_read_b128 v[220:223], v146 offset:39936
	global_load_lds_dwordx4 v[232:233], off
	v_lshl_add_u64 v[232:233], s[20:21], 0, v[132:133]
	s_mov_b32 m0, s54
	s_nop 0
	global_load_lds_dwordx4 v[232:233], off
	s_waitcnt vmcnt(8)
	s_waitcnt lgkmcnt(0)
	s_barrier
	s_setprio 0
	s_waitcnt lgkmcnt(0)
	v_mfma_f32_16x16x32_bf16 v[126:129], v[160:163], v[192:195], v[126:129]
	v_mfma_f32_16x16x32_bf16 v[122:125], v[168:171], v[192:195], v[122:125]
	v_mfma_f32_16x16x32_bf16 v[110:113], v[160:163], v[200:203], v[110:113]
	v_mfma_f32_16x16x32_bf16 v[106:109], v[168:171], v[200:203], v[106:109]
	v_mfma_f32_16x16x32_bf16 v[94:97], v[160:163], v[208:211], v[94:97]
	v_mfma_f32_16x16x32_bf16 v[90:93], v[168:171], v[208:211], v[90:93]
	v_mfma_f32_16x16x32_bf16 v[78:81], v[160:163], v[216:219], v[78:81]
	v_mfma_f32_16x16x32_bf16 v[74:77], v[168:171], v[216:219], v[74:77]
	v_mfma_f32_16x16x32_bf16 v[126:129], v[164:167], v[196:199], v[126:129]
	v_mfma_f32_16x16x32_bf16 v[122:125], v[172:175], v[196:199], v[122:125]
	v_mfma_f32_16x16x32_bf16 v[110:113], v[164:167], v[204:207], v[110:113]
	v_mfma_f32_16x16x32_bf16 v[106:109], v[172:175], v[204:207], v[106:109]
	v_mfma_f32_16x16x32_bf16 v[94:97], v[164:167], v[212:215], v[94:97]
	v_mfma_f32_16x16x32_bf16 v[90:93], v[172:175], v[212:215], v[90:93]
	v_mfma_f32_16x16x32_bf16 v[78:81], v[164:167], v[220:223], v[78:81]
	v_mfma_f32_16x16x32_bf16 v[74:77], v[172:175], v[220:223], v[74:77]
	v_mfma_f32_16x16x32_bf16 v[118:121], v[176:179], v[192:195], v[118:121]
	v_mfma_f32_16x16x32_bf16 v[114:117], v[184:187], v[192:195], v[114:117]
	v_mfma_f32_16x16x32_bf16 v[102:105], v[176:179], v[200:203], v[102:105]
	v_mfma_f32_16x16x32_bf16 v[98:101], v[184:187], v[200:203], v[98:101]
	v_mfma_f32_16x16x32_bf16 v[86:89], v[176:179], v[208:211], v[86:89]
	v_mfma_f32_16x16x32_bf16 v[82:85], v[184:187], v[208:211], v[82:85]
	v_mfma_f32_16x16x32_bf16 v[70:73], v[176:179], v[216:219], v[70:73]
	v_mfma_f32_16x16x32_bf16 v[66:69], v[184:187], v[216:219], v[66:69]
	v_mfma_f32_16x16x32_bf16 v[118:121], v[180:183], v[196:199], v[118:121]
	v_mfma_f32_16x16x32_bf16 v[114:117], v[188:191], v[196:199], v[114:117]
	v_mfma_f32_16x16x32_bf16 v[102:105], v[180:183], v[204:207], v[102:105]
	v_mfma_f32_16x16x32_bf16 v[98:101], v[188:191], v[204:207], v[98:101]
	v_mfma_f32_16x16x32_bf16 v[86:89], v[180:183], v[212:215], v[86:89]
	v_mfma_f32_16x16x32_bf16 v[82:85], v[188:191], v[212:215], v[82:85]
	v_mfma_f32_16x16x32_bf16 v[70:73], v[180:183], v[220:223], v[70:73]
	v_mfma_f32_16x16x32_bf16 v[66:69], v[188:191], v[220:223], v[66:69]
	s_setprio 1
	s_barrier
	s_add_i32 s20, s67, s30
	v_lshl_add_u64 v[140:141], v[140:141], 0, s[94:95]
	s_mov_b32 m0, s20
	ds_read_b128 v[192:195], v146 offset:49152
	ds_read_b128 v[196:199], v146 offset:50176
	ds_read_b128 v[200:203], v146 offset:51200
	ds_read_b128 v[204:207], v146 offset:52224
	ds_read_b128 v[208:211], v146 offset:53248
	ds_read_b128 v[212:215], v146 offset:54272
	ds_read_b128 v[216:219], v146 offset:55296
	ds_read_b128 v[220:223], v146 offset:56320
	global_load_lds_dwordx4 v[140:141], off
	v_lshl_add_u64 v[140:141], v[148:149], 0, s[94:95]
	s_add_i32 m0, s20, 0x2000
	s_add_i32 s20, s70, s30
	global_load_lds_dwordx4 v[140:141], off
	v_lshl_add_u64 v[140:141], v[224:225], 0, s[94:95]
	s_mov_b32 m0, s20
	s_nop 0
	global_load_lds_dwordx4 v[140:141], off
	v_lshl_add_u64 v[140:141], v[226:227], 0, s[94:95]
	s_add_i32 m0, s20, 0x2000
	s_nop 0
	global_load_lds_dwordx4 v[140:141], off
	v_lshl_add_u64 v[140:141], v[228:229], 0, s[94:95]
	s_mov_b32 m0, s55
	s_nop 0
	global_load_lds_dwordx4 v[140:141], off
	v_lshl_add_u64 v[140:141], v[230:231], 0, s[94:95]
	s_mov_b32 m0, s56
	s_nop 0
	global_load_lds_dwordx4 v[140:141], off
	s_waitcnt vmcnt(8)
	s_waitcnt lgkmcnt(0)
	s_barrier
	s_setprio 0
	s_waitcnt lgkmcnt(0)
	v_mfma_f32_16x16x32_bf16 v[62:65], v[160:163], v[192:195], v[62:65]
	v_mfma_f32_16x16x32_bf16 v[58:61], v[168:171], v[192:195], v[58:61]
	v_mfma_f32_16x16x32_bf16 v[46:49], v[160:163], v[200:203], v[46:49]
	v_mfma_f32_16x16x32_bf16 v[42:45], v[168:171], v[200:203], v[42:45]
	v_mfma_f32_16x16x32_bf16 v[30:33], v[160:163], v[208:211], v[30:33]
	v_mfma_f32_16x16x32_bf16 v[26:29], v[168:171], v[208:211], v[26:29]
	v_mfma_f32_16x16x32_bf16 v[14:17], v[160:163], v[216:219], v[14:17]
	v_mfma_f32_16x16x32_bf16 v[10:13], v[168:171], v[216:219], v[10:13]
	v_mfma_f32_16x16x32_bf16 v[62:65], v[164:167], v[196:199], v[62:65]
	v_mfma_f32_16x16x32_bf16 v[58:61], v[172:175], v[196:199], v[58:61]
	v_mfma_f32_16x16x32_bf16 v[46:49], v[164:167], v[204:207], v[46:49]
	v_mfma_f32_16x16x32_bf16 v[42:45], v[172:175], v[204:207], v[42:45]
	v_mfma_f32_16x16x32_bf16 v[30:33], v[164:167], v[212:215], v[30:33]
	v_mfma_f32_16x16x32_bf16 v[26:29], v[172:175], v[212:215], v[26:29]
	v_mfma_f32_16x16x32_bf16 v[14:17], v[164:167], v[220:223], v[14:17]
	v_mfma_f32_16x16x32_bf16 v[10:13], v[172:175], v[220:223], v[10:13]
	v_mfma_f32_16x16x32_bf16 v[54:57], v[176:179], v[192:195], v[54:57]
	v_mfma_f32_16x16x32_bf16 v[50:53], v[184:187], v[192:195], v[50:53]
	v_mfma_f32_16x16x32_bf16 v[38:41], v[176:179], v[200:203], v[38:41]
	v_mfma_f32_16x16x32_bf16 v[34:37], v[184:187], v[200:203], v[34:37]
	v_mfma_f32_16x16x32_bf16 v[22:25], v[176:179], v[208:211], v[22:25]
	v_mfma_f32_16x16x32_bf16 v[18:21], v[184:187], v[208:211], v[18:21]
	v_mfma_f32_16x16x32_bf16 v[6:9], v[176:179], v[216:219], v[6:9]
	v_mfma_f32_16x16x32_bf16 v[2:5], v[184:187], v[216:219], v[2:5]
	v_mfma_f32_16x16x32_bf16 v[54:57], v[180:183], v[196:199], v[54:57]
	v_mfma_f32_16x16x32_bf16 v[50:53], v[188:191], v[196:199], v[50:53]
	v_mfma_f32_16x16x32_bf16 v[38:41], v[180:183], v[204:207], v[38:41]
	v_mfma_f32_16x16x32_bf16 v[34:37], v[188:191], v[204:207], v[34:37]
	v_mfma_f32_16x16x32_bf16 v[22:25], v[180:183], v[212:215], v[22:25]
	v_mfma_f32_16x16x32_bf16 v[18:21], v[188:191], v[212:215], v[18:21]
	v_mfma_f32_16x16x32_bf16 v[6:9], v[180:183], v[220:223], v[6:9]
	v_mfma_f32_16x16x32_bf16 v[2:5], v[188:191], v[220:223], v[2:5]
	s_setprio 1
	s_barrier
	s_add_u32 s16, s16, 0x100
	s_addc_u32 s17, s17, 0
	s_add_u32 s64, s64, 0x100
	s_addc_u32 s65, s65, 0
	s_cmp_ge_u32 s66, s57
	s_mov_b32 s20, s66
	s_cbranch_scc0 .LBB0_419
	s_and_b64 vcc, exec, s[10:11]
	s_cbranch_vccz .LBB0_422
	s_barrier
